# odd-layer attention: QK MFMA chain at s_setprio 1, exp/PV section at setprio 0 (on top of v5)
# speedup vs baseline: 1.0063x; 1.0063x over previous
; __device__ __forceinline__ float fexp2(float x) { return __builtin_amdgcn_exp2f(x); }
; #define MFMA(a, b, c) __builtin_amdgcn_mfma_f32_32x32x16_bf16((a), (b), (c), 0, 0, 0)
; #define LOADKV(t) do { \
;     _Pragma("unroll") for (int j = 0; j < NKC; ++j) if (j + 1 < NKC || k1) rk[j] = *(const u32x4*)(kh + (size_t)(t) * 64 * DQK + (size_t)(tid + 512 * j) * 8); \
;     _Pragma("unroll") for (int j = 0; j < NVC; ++j) rv[j] = *(const u32x4*)(vg0 + (size_t)(64 * j) * S + (size_t)(t) * 64); } while (0)
; #define STOREKV(slot) do { \
;     _Pragma("unroll") for (int j = 0; j < NKC; ++j) if (j + 1 < NKC || k1) *(u32x4*)(sK + (slot) * KSB + klo[j]) = rk[j]; \
;     _Pragma("unroll") for (int j = 0; j < NVC; ++j) *(u32x4*)(sV + (slot) * VSB + vlo[j]) = rv[j]; } while (0)
; template <int DQK, int DV>
; __device__ __forceinline__ void attn_pass2(const bf16_t* __restrict__ qh, const bf16_t* __restrict__ kh, const bf16_t* __restrict__ vth, int q0, char* smem, f32x16 (&o)[2][DV / 32], float kmax, int wvp) {
;     ...
;   for (int kt = 0; kt < NT; ++kt) {
;     const int cur = kt & 1;
;     __syncthreads();
;     if (kt + 1 < NT) { STOREKV(cur ^ 1); if (kt + 2 < NT) LOADKV(kt + 2); }
;     f32x16 s[2][2];
;     const char* kb0 = sK + cur * KSB + kofs;
; #pragma unroll
;     for (int ks = 0; ks < NKS; ++ks) {
;       const bf16x8 a0 = *(const bf16x8*)(kb0 + ks * 32), a1 = *(const bf16x8*)(kb0 + 32 * KP + ks * 32);
; #pragma unroll
;       for (int qb = 0; qb < 2; ++qb) {
;         if (ks == 0) {
;           f32x16 z;
; #pragma unroll
;           for (int i = 0; i < 16; ++i) z[i] = 0.f;
;           s[qb][0] = MFMA(a0, qf[qb][0], z); s[qb][1] = MFMA(a1, qf[qb][0], z);
;         } else { s[qb][0] = MFMA(a0, qf[qb][ks], s[qb][0]); s[qb][1] = MFMA(a1, qf[qb][ks], s[qb][1]); }
;       }
;     }
;     __builtin_amdgcn_sched_barrier(0);
; #pragma unroll
;     for (int qb = 0; qb < 2; ++qb) {
;       float rs0 = 0.f, rs1 = 0.f;
; #pragma unroll
;       for (int i = 0; i < 16; ++i) { s[qb][0][i] = fexp2(s[qb][0][i] - mref[qb]); s[qb][1][i] = fexp2(s[qb][1][i] - mref[qb]); rs0 += s[qb][0][i]; rs1 += s[qb][1][i]; }
;       l_run[qb] += rs0 + rs1;
;     }
.LBB0_1429:
	s_mulk_i32 s7, 0x2400
	v_add_u32_e32 v180, s7, v169
	s_setprio 1
	ds_read_b128 v[64:67], v180
	ds_read_b128 v[176:179], v180 offset:32
	ds_read_b128 v[68:71], v180 offset:4608
	ds_read_b128 v[192:195], v180 offset:4640
	s_add_i32 s6, s6, 1
	s_waitcnt lgkmcnt(3)
	v_mfma_f32_32x32x16_bf16 v[112:127], v[64:67], v[128:131], v[236:251]
	s_waitcnt lgkmcnt(1)
	v_mfma_f32_32x32x16_bf16 v[96:111], v[68:71], v[128:131], v[236:251]
	v_mfma_f32_32x32x16_bf16 v[80:95], v[64:67], v[144:147], v[236:251]
	v_mfma_f32_32x32x16_bf16 v[64:79], v[68:71], v[144:147], v[236:251]
	v_mfma_f32_32x32x16_bf16 v[112:127], v[176:179], v[132:135], v[112:127]
	s_waitcnt lgkmcnt(0)
	v_mfma_f32_32x32x16_bf16 v[96:111], v[192:195], v[132:135], v[96:111]
	v_mfma_f32_32x32x16_bf16 v[80:95], v[176:179], v[148:151], v[80:95]
	v_mfma_f32_32x32x16_bf16 v[64:79], v[192:195], v[148:151], v[64:79]
	ds_read_b128 v[176:179], v180 offset:64
	ds_read_b128 v[192:195], v180 offset:96
	ds_read_b128 v[196:199], v180 offset:4672
	ds_read_b128 v[200:203], v180 offset:4704
	s_waitcnt lgkmcnt(3)
	v_mfma_f32_32x32x16_bf16 v[112:127], v[176:179], v[136:139], v[112:127]
	s_waitcnt lgkmcnt(1)
	v_mfma_f32_32x32x16_bf16 v[96:111], v[196:199], v[136:139], v[96:111]
	v_mfma_f32_32x32x16_bf16 v[80:95], v[176:179], v[152:155], v[80:95]
	v_mfma_f32_32x32x16_bf16 v[64:79], v[196:199], v[152:155], v[64:79]
	v_mfma_f32_32x32x16_bf16 v[112:127], v[192:195], v[140:143], v[112:127]
	s_waitcnt lgkmcnt(0)
	v_mfma_f32_32x32x16_bf16 v[96:111], v[200:203], v[140:143], v[96:111]
	v_mfma_f32_32x32x16_bf16 v[80:95], v[192:195], v[156:159], v[80:95]
	v_mfma_f32_32x32x16_bf16 v[64:79], v[200:203], v[156:159], v[64:79]
	s_setprio 0
	s_nop 9
	v_exp_f32_e32 v186, v96
	v_exp_f32_e32 v97, v97
	v_exp_f32_e32 v177, v112
	v_exp_f32_e32 v113, v113
	v_exp_f32_e32 v179, v114
	v_exp_f32_e32 v187, v98
	v_add_f32_e32 v98, v97, v186
	v_exp_f32_e32 v115, v115
	v_exp_f32_e32 v190, v99
	v_exp_f32_e32 v204, v100
	v_exp_f32_e32 v99, v116
	v_exp_f32_e32 v117, v117
	v_add_f32_e32 v96, v113, v177
	v_exp_f32_e32 v101, v101
	v_add_f32_e32 v96, v179, v96
	v_exp_f32_e32 v181, v118
	v_add_f32_e32 v96, v115, v96
	v_add_f32_e32 v96, v99, v96
	v_add_f32_e32 v96, v117, v96
	v_add_f32_e32 v112, v181, v96
	v_exp_f32_e32 v176, v119
	v_exp_f32_e32 v178, v103
	v_add_f32_e32 v98, v187, v98
	v_exp_f32_e32 v205, v102
	v_exp_f32_e32 v180, v120
	v_exp_f32_e32 v96, v104
	v_exp_f32_e32 v104, v123
	v_add_f32_e32 v98, v190, v98
	v_exp_f32_e32 v100, v106
	v_exp_f32_e32 v106, v107
	v_add_f32_e32 v98, v204, v98
	v_exp_f32_e32 v118, v124
	v_add_f32_e32 v98, v101, v98
	v_exp_f32_e32 v120, v108
	v_add_f32_e32 v102, v205, v98
	v_exp_f32_e32 v124, v125
	v_exp_f32_e32 v116, v121
	v_exp_f32_e32 v108, v109
	v_exp_f32_e32 v114, v105
	v_exp_f32_e32 v98, v122
	v_exp_f32_e32 v122, v126
	v_exp_f32_e32 v110, v110
	v_exp_f32_e32 v126, v127
	v_exp_f32_e32 v103, v80
	v_exp_f32_e32 v107, v64
	v_exp_f32_e32 v109, v81
	v_exp_f32_e32 v65, v65
	v_exp_f32_e32 v121, v66
	v_add_f32_e32 v66, v109, v103
	v_add_f32_e32 v80, v65, v107
	v_add_f32_e32 v206, v121, v80
	v_exp_f32_e32 v207, v83
	v_add_u32_e32 v209, s7, v185
	v_exp_f32_e32 v64, v111
	v_exp_f32_e32 v111, v82
	v_exp_f32_e32 v208, v84
	ds_read_b128 v[80:83], v209 offset:18432
	ds_read_b128 v[196:199], v209 offset:18464
	ds_read_b128 v[200:203], v209 offset:23040
	v_exp_f32_e32 v212, v85
	v_exp_f32_e32 v213, v86
	v_cvt_pk_bf16_f32 v192, v177, v113
	v_exp_f32_e32 v177, v87
	v_cvt_pk_bf16_f32 v84, v103, v109
	v_exp_f32_e32 v109, v67
	v_add_f32_e32 v66, v111, v66
	v_cvt_pk_bf16_f32 v85, v111, v207
	v_exp_f32_e32 v111, v68
	v_cvt_pk_bf16_f32 v195, v181, v176
	v_exp_f32_e32 v181, v88
	v_cvt_pk_bf16_f32 v194, v99, v117
	v_exp_f32_e32 v117, v89
	v_cvt_pk_bf16_f32 v193, v179, v115
	v_cvt_pk_bf16_f32 v86, v208, v212
	v_cvt_pk_bf16_f32 v87, v213, v177
	v_exp_f32_e32 v99, v90
	s_waitcnt lgkmcnt(2)
	v_mfma_f32_32x32x16_bf16 v[48:63], v[80:83], v[192:195], v[48:63]
	v_exp_f32_e32 v105, v91
	v_exp_f32_e32 v119, v92
	v_exp_f32_e32 v125, v93
	v_mfma_f32_32x32x16_bf16 v[16:31], v[80:83], v[84:87], v[16:31]
	ds_read_b128 v[80:83], v209 offset:23072
	v_exp_f32_e32 v123, v94
	v_exp_f32_e32 v92, v69
	v_exp_f32_e32 v127, v95
	s_waitcnt lgkmcnt(1)
; __device__ __forceinline__ unsigned pk2(float lo, float hi) { f32x2_t v = {lo, hi}; bf16x2_t b = __builtin_convertvector(v, bf16x2_t); return __builtin_bit_cast(unsigned, b); }
; __device__ __forceinline__ float fexp2(float x) { return __builtin_amdgcn_exp2f(x); }
; #define MFMA(a, b, c) __builtin_amdgcn_mfma_f32_32x32x16_bf16((a), (b), (c), 0, 0, 0)
; template <int DQK, int DV>
; __device__ __forceinline__ void attn_pass2(const bf16_t* __restrict__ qh, const bf16_t* __restrict__ kh, const bf16_t* __restrict__ vth, int q0, char* smem, f32x16 (&o)[2][DV / 32], float kmax, int wvp) {
;     ...
; #pragma unroll
;     for (int qb = 0; qb < 2; ++qb) {
;       float rs0 = 0.f, rs1 = 0.f;
; #pragma unroll
;       for (int i = 0; i < 16; ++i) { s[qb][0][i] = fexp2(s[qb][0][i] - mref[qb]); s[qb][1][i] = fexp2(s[qb][1][i] - mref[qb]); rs0 += s[qb][0][i]; rs1 += s[qb][1][i]; }
;       l_run[qb] += rs0 + rs1;
;     }
;     const char* vb0 = sV + cur * VSB + vofs;
; #pragma unroll
;     for (int kb = 0; kb < 2; ++kb)
; #pragma unroll
;       for (int s2 = 0; s2 < 2; ++s2) {
;         bf16x8 pq[2];
; #pragma unroll
;         for (int qb = 0; qb < 2; ++qb) {
;           u32x4 w;
;           w.x = pk2(s[qb][kb][8 * s2 + 0], s[qb][kb][8 * s2 + 1]); w.y = pk2(s[qb][kb][8 * s2 + 2], s[qb][kb][8 * s2 + 3]);
;           w.z = pk2(s[qb][kb][8 * s2 + 4], s[qb][kb][8 * s2 + 5]); w.w = pk2(s[qb][kb][8 * s2 + 6], s[qb][kb][8 * s2 + 7]);
;           pq[qb] = __builtin_bit_cast(bf16x8, w);
;         }
; #pragma unroll
;         for (int eb = 0; eb < NEB; ++eb) {
;           const bf16x8 a = *(const bf16x8*)(vb0 + eb * 32 * VP + (32 * kb + 16 * s2) * 2);
; #pragma unroll
;           for (int qb = 0; qb < 2; ++qb) o[qb][eb] = MFMA(a, pq[qb], o[qb][eb]);
;         }
;       }
;   }
	v_mfma_f32_32x32x16_bf16 v[0:15], v[200:203], v[84:87], v[0:15]
	v_exp_f32_e32 v93, v70
	v_add_f32_e32 v66, v207, v66
	v_add_f32_e32 v67, v109, v206
	v_add_f32_e32 v66, v208, v66
	v_add_f32_e32 v67, v111, v67
	v_add_f32_e32 v66, v212, v66
	v_add_f32_e32 v67, v92, v67
	v_mfma_f32_32x32x16_bf16 v[32:47], v[200:203], v[192:195], v[32:47]
	v_cvt_pk_bf16_f32 v84, v180, v116
	v_cvt_pk_bf16_f32 v85, v98, v104
	v_cvt_pk_bf16_f32 v86, v118, v124
	v_cvt_pk_bf16_f32 v87, v122, v126
	v_cvt_pk_bf16_f32 v88, v181, v117
	v_cvt_pk_bf16_f32 v89, v99, v105
	v_cvt_pk_bf16_f32 v90, v119, v125
	v_cvt_pk_bf16_f32 v91, v123, v127
	v_add_f32_e32 v113, v213, v66
	v_add_f32_e32 v103, v93, v67
	ds_read_b128 v[66:69], v209 offset:18496
	v_mfma_f32_32x32x16_bf16 v[48:63], v[196:199], v[84:87], v[48:63]
	v_exp_f32_e32 v179, v71
	v_mov_b32_e32 v70, v72
	v_exp_f32_e32 v115, v73
	v_cvt_pk_bf16_f32 v71, v121, v109
	v_cvt_pk_bf16_f32 v72, v111, v92
	v_cvt_pk_bf16_f32 v73, v93, v179
	v_mfma_f32_32x32x16_bf16 v[16:31], v[196:199], v[88:91], v[16:31]
	v_lshl_add_u64 v[170:171], v[170:171], 0, s[52:53]
	s_cmpk_lg_i32 s6, 0x80
	v_lshl_add_u64 v[172:173], v[172:173], 0, s[54:55]
	s_waitcnt lgkmcnt(1)
	v_mfma_f32_32x32x16_bf16 v[0:15], v[80:83], v[88:91], v[0:15]
	ds_read_b128 v[88:91], v209 offset:23104
	v_mfma_f32_32x32x16_bf16 v[32:47], v[80:83], v[84:87], v[32:47]
	v_cvt_pk_bf16_f32 v80, v186, v97
	v_exp_f32_e32 v97, v70
	v_cvt_pk_bf16_f32 v70, v107, v65
	v_cvt_pk_bf16_f32 v81, v187, v190
	v_cvt_pk_bf16_f32 v82, v204, v101
	v_cvt_pk_bf16_f32 v83, v205, v178
	v_exp_f32_e32 v101, v74
	ds_read_b128 v[84:87], v209 offset:18528
	s_waitcnt lgkmcnt(2)
	v_mfma_f32_32x32x16_bf16 v[48:63], v[66:69], v[80:83], v[48:63]
	v_exp_f32_e32 v107, v75
	v_exp_f32_e32 v121, v76
	v_exp_f32_e32 v109, v77
	v_exp_f32_e32 v111, v78
	v_mfma_f32_32x32x16_bf16 v[16:31], v[66:69], v[70:73], v[16:31]
	ds_read_b128 v[66:69], v209 offset:23136
	v_exp_f32_e32 v65, v79
	v_add_f32_e32 v74, v178, v102
	v_add_f32_e32 v75, v179, v103
	s_nop 0
	v_add_f32_e32 v74, v96, v74
	v_add_f32_e32 v75, v97, v75
	s_waitcnt lgkmcnt(2)
	v_mfma_f32_32x32x16_bf16 v[32:47], v[88:91], v[80:83], v[32:47]
	v_add_f32_e64 v80, v114, v74
	v_add_f32_e64 v81, v115, v75
	v_cvt_pk_bf16_f32 v74, v97, v115
	v_cvt_pk_bf16_f32 v75, v101, v107
	v_add_f32_e64 v80, v100, v80
	v_add_f32_e64 v81, v101, v81
	v_add_f32_e32 v80, v106, v80
	v_add_f32_e32 v81, v107, v81
	v_mfma_f32_32x32x16_bf16 v[0:15], v[88:91], v[70:73], v[0:15]
	v_add_f32_e64 v70, v176, v112
	v_add_f32_e64 v71, v177, v113
	v_cvt_pk_bf16_f32 v72, v120, v108
	v_add_f32_e64 v76, v180, v70
	v_add_f32_e64 v77, v181, v71
	v_cvt_pk_bf16_f32 v70, v96, v114
	v_cvt_pk_bf16_f32 v71, v100, v106
	v_cvt_pk_bf16_f32 v73, v110, v64
	v_add_f32_e32 v78, v116, v76
	v_add_f32_e32 v79, v117, v77
	v_cvt_pk_bf16_f32 v76, v121, v109
	v_cvt_pk_bf16_f32 v77, v111, v65
	s_waitcnt lgkmcnt(1)
	v_mfma_f32_32x32x16_bf16 v[48:63], v[84:87], v[70:73], v[48:63]
	v_add_f32_e64 v78, v98, v78
	v_add_f32_e64 v79, v99, v79
	v_add_f32_e64 v80, v120, v80
	v_add_f32_e64 v81, v121, v81
	v_add_f32_e64 v78, v104, v78
	v_add_f32_e64 v79, v105, v79
	v_add_f32_e32 v78, v118, v78
	v_add_f32_e32 v79, v119, v79
	s_nop 0
	v_add_f32_e32 v78, v124, v78
	v_add_f32_e32 v79, v125, v79
	v_mfma_f32_32x32x16_bf16 v[16:31], v[84:87], v[74:77], v[16:31]
	s_waitcnt lgkmcnt(0)
	v_mfma_f32_32x32x16_bf16 v[32:47], v[66:69], v[70:73], v[32:47]
	v_add_f32_e64 v70, v108, v80
	v_add_f32_e64 v71, v109, v81
	v_add_f32_e64 v72, v122, v78
	v_add_f32_e64 v73, v123, v79
	v_add_f32_e64 v70, v110, v70
	v_add_f32_e64 v71, v111, v71
	v_add_f32_e32 v72, v126, v72
	v_add_f32_e32 v73, v127, v73
	v_add_f32_e32 v64, v64, v70
	v_add_f32_e32 v65, v65, v71
	s_nop 0
	v_add_f32_e32 v64, v72, v64
	v_add_f32_e32 v65, v73, v65
	v_mfma_f32_32x32x16_bf16 v[0:15], v[66:69], v[74:77], v[0:15]
	v_add_f32_e64 v174, v174, v64
	v_add_f32_e64 v175, v175, v65
	s_cbranch_scc0 .LBB0_1433

; __device__ __forceinline__ float fexp2(float x) { return __builtin_amdgcn_exp2f(x); }
; #define MFMA(a, b, c) __builtin_amdgcn_mfma_f32_32x32x16_bf16((a), (b), (c), 0, 0, 0)
; #define LOADKV(t) do { \
;     _Pragma("unroll") for (int j = 0; j < NKC; ++j) if (j + 1 < NKC || k1) rk[j] = *(const u32x4*)(kh + (size_t)(t) * 64 * DQK + (size_t)(tid + 512 * j) * 8); \
;     _Pragma("unroll") for (int j = 0; j < NVC; ++j) rv[j] = *(const u32x4*)(vg0 + (size_t)(64 * j) * S + (size_t)(t) * 64); } while (0)
; #define STOREKV(slot) do { \
;     _Pragma("unroll") for (int j = 0; j < NKC; ++j) if (j + 1 < NKC || k1) *(u32x4*)(sK + (slot) * KSB + klo[j]) = rk[j]; \
;     _Pragma("unroll") for (int j = 0; j < NVC; ++j) *(u32x4*)(sV + (slot) * VSB + vlo[j]) = rv[j]; } while (0)
; template <int DQK, int DV>
; __device__ __forceinline__ void attn_pass2(const bf16_t* __restrict__ qh, const bf16_t* __restrict__ kh, const bf16_t* __restrict__ vth, int q0, char* smem, f32x16 (&o)[2][DV / 32], float kmax, int wvp) {
;     ...
;   for (int kt = 0; kt < NT; ++kt) {
;     const int cur = kt & 1;
;     __syncthreads();
;     if (kt + 1 < NT) { STOREKV(cur ^ 1); if (kt + 2 < NT) LOADKV(kt + 2); }
;     f32x16 s[2][2];
;     const char* kb0 = sK + cur * KSB + kofs;
; #pragma unroll
;     for (int ks = 0; ks < NKS; ++ks) {
;       const bf16x8 a0 = *(const bf16x8*)(kb0 + ks * 32), a1 = *(const bf16x8*)(kb0 + 32 * KP + ks * 32);
; #pragma unroll
;       for (int qb = 0; qb < 2; ++qb) {
;         if (ks == 0) {
;           f32x16 z;
; #pragma unroll
;           for (int i = 0; i < 16; ++i) z[i] = 0.f;
;           s[qb][0] = MFMA(a0, qf[qb][0], z); s[qb][1] = MFMA(a1, qf[qb][0], z);
;         } else { s[qb][0] = MFMA(a0, qf[qb][ks], s[qb][0]); s[qb][1] = MFMA(a1, qf[qb][ks], s[qb][1]); }
;       }
;     }
;     __builtin_amdgcn_sched_barrier(0);
; #pragma unroll
;     for (int qb = 0; qb < 2; ++qb) {
;       float rs0 = 0.f, rs1 = 0.f;
; #pragma unroll
;       for (int i = 0; i < 16; ++i) { s[qb][0][i] = fexp2(s[qb][0][i] - mref[qb]); s[qb][1][i] = fexp2(s[qb][1][i] - mref[qb]); rs0 += s[qb][0][i]; rs1 += s[qb][1][i]; }
;       l_run[qb] += rs0 + rs1;
;     }
.LBB0_1445:
	s_mul_i32 s8, s11, 0x3400
	v_add_u32_e32 v190, s8, v215
	s_setprio 1
	ds_read_b128 v[64:67], v190
	ds_read_b128 v[202:205], v190 offset:32
	ds_read_b128 v[68:71], v190 offset:6656
	ds_read_b128 v[206:209], v190 offset:6688
	s_waitcnt lgkmcnt(3)
	v_mfma_f32_32x32x16_bf16 v[112:127], v[64:67], v[128:131], v[236:251]
	s_waitcnt lgkmcnt(1)
	v_mfma_f32_32x32x16_bf16 v[96:111], v[68:71], v[128:131], v[236:251]
	v_mfma_f32_32x32x16_bf16 v[80:95], v[64:67], v[152:155], v[236:251]
	v_mfma_f32_32x32x16_bf16 v[64:79], v[68:71], v[152:155], v[236:251]
	v_mfma_f32_32x32x16_bf16 v[112:127], v[202:205], v[132:135], v[112:127]
	s_waitcnt lgkmcnt(0)
	v_mfma_f32_32x32x16_bf16 v[96:111], v[206:209], v[132:135], v[96:111]
	v_mfma_f32_32x32x16_bf16 v[80:95], v[202:205], v[156:159], v[80:95]
	v_mfma_f32_32x32x16_bf16 v[64:79], v[206:209], v[156:159], v[64:79]
	ds_read_b128 v[202:205], v190 offset:64
	ds_read_b128 v[206:209], v190 offset:96
	ds_read_b128 v[218:221], v190 offset:6720
	ds_read_b128 v[222:225], v190 offset:6752
	s_waitcnt lgkmcnt(3)
	v_mfma_f32_32x32x16_bf16 v[112:127], v[202:205], v[136:139], v[112:127]
	s_waitcnt lgkmcnt(1)
	v_mfma_f32_32x32x16_bf16 v[96:111], v[218:221], v[136:139], v[96:111]
	v_mfma_f32_32x32x16_bf16 v[80:95], v[202:205], v[160:163], v[80:95]
	v_mfma_f32_32x32x16_bf16 v[64:79], v[218:221], v[160:163], v[64:79]
	v_mfma_f32_32x32x16_bf16 v[112:127], v[206:209], v[140:143], v[112:127]
	s_waitcnt lgkmcnt(0)
	v_mfma_f32_32x32x16_bf16 v[96:111], v[222:225], v[140:143], v[96:111]
	v_mfma_f32_32x32x16_bf16 v[80:95], v[206:209], v[164:167], v[80:95]
	ds_read_b128 v[202:205], v190 offset:128
	ds_read_b128 v[206:209], v190 offset:160
	v_mfma_f32_32x32x16_bf16 v[64:79], v[222:225], v[164:167], v[64:79]
	ds_read_b128 v[218:221], v190 offset:6784
	ds_read_b128 v[222:225], v190 offset:6816
	s_waitcnt lgkmcnt(3)
	v_mfma_f32_32x32x16_bf16 v[112:127], v[202:205], v[144:147], v[112:127]
	s_waitcnt lgkmcnt(1)
	v_mfma_f32_32x32x16_bf16 v[96:111], v[218:221], v[144:147], v[96:111]
	v_mfma_f32_32x32x16_bf16 v[80:95], v[202:205], v[168:171], v[80:95]
	v_mfma_f32_32x32x16_bf16 v[64:79], v[218:221], v[168:171], v[64:79]
	v_mfma_f32_32x32x16_bf16 v[112:127], v[206:209], v[148:151], v[112:127]
	s_waitcnt lgkmcnt(0)
	v_mfma_f32_32x32x16_bf16 v[96:111], v[222:225], v[148:151], v[96:111]
	v_mfma_f32_32x32x16_bf16 v[80:95], v[206:209], v[172:175], v[80:95]
	v_mfma_f32_32x32x16_bf16 v[64:79], v[222:225], v[172:175], v[64:79]
	s_setprio 0
	s_nop 9
	v_exp_f32_e32 v96, v96
	v_exp_f32_e32 v112, v112
	v_exp_f32_e32 v208, v97
	v_exp_f32_e32 v204, v113
	v_exp_f32_e32 v227, v99
	v_exp_f32_e32 v114, v114
	v_exp_f32_e32 v116, v116
	v_exp_f32_e32 v217, v98
	v_exp_f32_e32 v100, v100
	v_add_f32_e32 v98, v208, v96
	v_exp_f32_e32 v202, v117
	v_add_f32_e32 v97, v204, v112
	v_exp_f32_e32 v190, v115
	v_exp_f32_e32 v228, v101
	v_exp_f32_e32 v118, v118
	v_add_f32_e32 v98, v217, v98
	v_exp_f32_e32 v229, v102
	v_add_f32_e32 v97, v114, v97
	v_add_f32_e32 v98, v227, v98
	v_add_f32_e32 v97, v190, v97
	v_add_f32_e32 v98, v100, v98
	v_add_f32_e32 v97, v116, v97
	v_add_f32_e32 v98, v228, v98
	v_add_f32_e32 v97, v202, v97
	v_add_f32_e32 v113, v229, v98
	v_add_f32_e32 v115, v118, v97
	v_exp_f32_e32 v203, v119
	v_exp_f32_e32 v119, v121
	v_exp_f32_e32 v117, v105
	v_exp_f32_e32 v99, v122
	v_exp_f32_e32 v101, v106
	v_exp_f32_e32 v205, v103
	v_exp_f32_e32 v103, v123
	v_exp_f32_e32 v105, v107
	v_exp_f32_e32 v107, v124
	v_exp_f32_e32 v121, v108
	v_exp_f32_e32 v125, v125
	v_exp_f32_e32 v109, v109
	v_exp_f32_e32 v123, v126
	v_exp_f32_e32 v209, v110
	v_exp_f32_e32 v127, v127
	v_exp_f32_e32 v98, v80
	v_exp_f32_e32 v102, v81
	v_exp_f32_e32 v108, v65
	v_exp_f32_e32 v207, v120
	v_exp_f32_e32 v97, v104
	v_exp_f32_e32 v104, v64
	v_exp_f32_e32 v106, v82
	v_exp_f32_e32 v111, v111
	v_exp_f32_e32 v110, v66
	v_add_f32_e32 v64, v102, v98
	v_add_f32_e32 v120, v106, v64
	s_mulk_i32 s11, 0x2400
	v_add_f32_e32 v65, v108, v104
	v_exp_f32_e32 v231, v83
	v_add_u32_e32 v233, s11, v216
	v_add_f32_e32 v230, v110, v65
	v_mov_b32_e32 v122, v67
	v_exp_f32_e32 v232, v84
	ds_read_b128 v[64:67], v233 offset:26624
	ds_read_b128 v[218:221], v233 offset:26656
	v_exp_f32_e32 v234, v85
	ds_read_b128 v[222:225], v233 offset:31232
	v_exp_f32_e32 v235, v86
	v_cvt_pk_bf16_f32 v82, v116, v202
	v_exp_f32_e32 v202, v87
	v_cvt_pk_bf16_f32 v80, v112, v204
	v_cvt_pk_bf16_f32 v81, v114, v190
	v_cvt_pk_bf16_f32 v83, v118, v203
	v_cvt_pk_bf16_f32 v84, v98, v102
	v_cvt_pk_bf16_f32 v85, v106, v231
	v_cvt_pk_bf16_f32 v86, v232, v234
	v_cvt_pk_bf16_f32 v87, v235, v202
	s_waitcnt lgkmcnt(2)
; __device__ __forceinline__ unsigned pk2(float lo, float hi) { f32x2_t v = {lo, hi}; bf16x2_t b = __builtin_convertvector(v, bf16x2_t); return __builtin_bit_cast(unsigned, b); }
; #define MFMA(a, b, c) __builtin_amdgcn_mfma_f32_32x32x16_bf16((a), (b), (c), 0, 0, 0)
; template <int DQK, int DV>
; __device__ __forceinline__ void attn_pass2(const bf16_t* __restrict__ qh, const bf16_t* __restrict__ kh, const bf16_t* __restrict__ vth, int q0, char* smem, f32x16 (&o)[2][DV / 32], float kmax, int wvp) {
;     ...
;     const char* vb0 = sV + cur * VSB + vofs;
; #pragma unroll
;     for (int kb = 0; kb < 2; ++kb)
; #pragma unroll
;       for (int s2 = 0; s2 < 2; ++s2) {
;         bf16x8 pq[2];
; #pragma unroll
;         for (int qb = 0; qb < 2; ++qb) {
;           u32x4 w;
;           w.x = pk2(s[qb][kb][8 * s2 + 0], s[qb][kb][8 * s2 + 1]); w.y = pk2(s[qb][kb][8 * s2 + 2], s[qb][kb][8 * s2 + 3]);
;           w.z = pk2(s[qb][kb][8 * s2 + 4], s[qb][kb][8 * s2 + 5]); w.w = pk2(s[qb][kb][8 * s2 + 6], s[qb][kb][8 * s2 + 7]);
;           pq[qb] = __builtin_bit_cast(bf16x8, w);
;         }
; #pragma unroll
;         for (int eb = 0; eb < NEB; ++eb) {
;           const bf16x8 a = *(const bf16x8*)(vb0 + eb * 32 * VP + (32 * kb + 16 * s2) * 2);
; #pragma unroll
;           for (int qb = 0; qb < 2; ++qb) o[qb][eb] = MFMA(a, pq[qb], o[qb][eb]);
;         }
;       }
;   }
	v_mfma_f32_32x32x16_bf16 v[48:63], v[64:67], v[80:83], v[48:63]
	v_exp_f32_e32 v116, v122
	s_add_u32 s6, s6, 0x3000
	s_addc_u32 s7, s7, 0
	s_add_i32 s10, s10, 1
	v_mfma_f32_32x32x16_bf16 v[16:31], v[64:67], v[84:87], v[16:31]
	v_exp_f32_e32 v190, v68
	v_exp_f32_e32 v206, v88
	ds_read_b128 v[64:67], v233 offset:31264
	v_exp_f32_e32 v118, v89
	s_waitcnt lgkmcnt(1)
	v_mfma_f32_32x32x16_bf16 v[32:47], v[222:225], v[80:83], v[32:47]
	v_exp_f32_e32 v98, v90
	v_exp_f32_e32 v102, v91
	v_exp_f32_e32 v106, v92
	v_exp_f32_e32 v124, v93
	v_mfma_f32_32x32x16_bf16 v[0:15], v[222:225], v[84:87], v[0:15]
	v_exp_f32_e32 v122, v94
	v_exp_f32_e32 v89, v69
	v_exp_f32_e32 v126, v95
	v_exp_f32_e32 v90, v70
	v_cvt_pk_bf16_f32 v80, v207, v119
	v_cvt_pk_bf16_f32 v81, v99, v103
	v_cvt_pk_bf16_f32 v82, v107, v125
	v_cvt_pk_bf16_f32 v83, v123, v127
	v_add_f32_e32 v68, v231, v120
	v_add_f32_e32 v88, v116, v230
	v_mfma_f32_32x32x16_bf16 v[48:63], v[218:221], v[80:83], v[48:63]
	v_add_f32_e32 v68, v232, v68
	v_add_f32_e32 v88, v190, v88
	v_add_f32_e32 v68, v234, v68
	v_add_f32_e32 v69, v89, v88
	v_cvt_pk_bf16_f32 v84, v206, v118
	v_cvt_pk_bf16_f32 v85, v98, v102
	v_cvt_pk_bf16_f32 v86, v106, v124
	s_waitcnt lgkmcnt(0)
	v_mfma_f32_32x32x16_bf16 v[32:47], v[64:67], v[80:83], v[32:47]
	v_exp_f32_e32 v204, v71
	v_cvt_pk_bf16_f32 v87, v122, v126
	v_add_f32_e32 v114, v235, v68
	v_add_f32_e32 v112, v90, v69
	ds_read_b128 v[68:71], v233 offset:26688
	ds_read_b128 v[80:83], v233 offset:26720
	v_mfma_f32_32x32x16_bf16 v[16:31], v[218:221], v[84:87], v[16:31]
	s_cmp_lg_u32 s6, 0x180000
	v_lshl_add_u64 v[194:195], v[194:195], 0, s[54:55]
	v_mfma_f32_32x32x16_bf16 v[0:15], v[64:67], v[84:87], v[0:15]
	v_cvt_pk_bf16_f32 v86, v190, v89
	v_cvt_pk_bf16_f32 v87, v90, v204
	ds_read_b128 v[88:91], v233 offset:31296
	v_cvt_pk_bf16_f32 v64, v96, v208
	v_cvt_pk_bf16_f32 v65, v217, v227
	v_cvt_pk_bf16_f32 v66, v100, v228
	v_cvt_pk_bf16_f32 v67, v229, v205
	v_cvt_pk_bf16_f32 v84, v104, v108
	v_cvt_pk_bf16_f32 v85, v110, v116
	s_waitcnt lgkmcnt(2)
	v_mfma_f32_32x32x16_bf16 v[48:63], v[68:71], v[64:67], v[48:63]
	v_exp_f32_e32 v96, v72
	v_exp_f32_e32 v116, v73
	v_exp_f32_e32 v120, v76
	v_add_f32_e32 v72, v204, v112
	v_add_f32_e32 v73, v205, v113
	v_mfma_f32_32x32x16_bf16 v[16:31], v[68:71], v[84:87], v[16:31]
	v_exp_f32_e32 v100, v74
	v_exp_f32_e32 v104, v75
	ds_read_b128 v[68:71], v233 offset:31328
	v_add_f32_e32 v72, v96, v72
	v_add_f32_e32 v73, v97, v73
	s_waitcnt lgkmcnt(1)
	v_mfma_f32_32x32x16_bf16 v[32:47], v[88:91], v[64:67], v[32:47]
	v_exp_f32_e32 v108, v77
	v_exp_f32_e32 v208, v78
	v_exp_f32_e32 v110, v79
	v_add_f32_e32 v64, v202, v114
	v_add_f32_e32 v65, v203, v115
	v_mfma_f32_32x32x16_bf16 v[0:15], v[88:91], v[84:87], v[0:15]
	v_add_f32_e64 v74, v206, v64
	v_add_f32_e64 v75, v207, v65
	v_cvt_pk_bf16_f32 v64, v97, v117
	v_cvt_pk_bf16_f32 v65, v101, v105
	v_cvt_pk_bf16_f32 v66, v121, v109
	v_cvt_pk_bf16_f32 v67, v209, v111
	v_add_f32_e32 v76, v118, v74
	v_add_f32_e32 v77, v119, v75
	v_add_f32_e32 v78, v116, v72
	v_add_f32_e32 v79, v117, v73
	v_cvt_pk_bf16_f32 v72, v96, v116
	v_cvt_pk_bf16_f32 v73, v100, v104
	v_cvt_pk_bf16_f32 v74, v120, v108
	v_cvt_pk_bf16_f32 v75, v208, v110
	v_mfma_f32_32x32x16_bf16 v[48:63], v[80:83], v[64:67], v[48:63]
	v_add_f32_e64 v76, v98, v76
	v_add_f32_e64 v77, v99, v77
	v_add_f32_e64 v78, v100, v78
	v_add_f32_e64 v79, v101, v79
	v_add_f32_e64 v76, v102, v76
	v_add_f32_e64 v77, v103, v77
	v_add_f32_e32 v78, v104, v78
	v_add_f32_e32 v79, v105, v79
	v_add_f32_e32 v76, v106, v76
	v_add_f32_e32 v77, v107, v77
	v_add_f32_e32 v78, v120, v78
	v_add_f32_e32 v79, v121, v79
	v_add_f32_e32 v76, v124, v76
	v_add_f32_e32 v77, v125, v77
	v_mfma_f32_32x32x16_bf16 v[16:31], v[80:83], v[72:75], v[16:31]
	s_waitcnt lgkmcnt(0)
	v_mfma_f32_32x32x16_bf16 v[32:47], v[68:71], v[64:67], v[32:47]
	v_add_f32_e64 v64, v108, v78
	v_add_f32_e64 v65, v109, v79
	v_add_f32_e64 v66, v122, v76
	v_add_f32_e64 v67, v123, v77
	v_add_f32_e64 v64, v208, v64
	v_add_f32_e64 v65, v209, v65
	v_add_f32_e32 v66, v126, v66
	v_add_f32_e32 v67, v127, v67
	v_add_f32_e32 v64, v110, v64
	v_add_f32_e32 v65, v111, v65
	s_nop 0
	v_add_f32_e32 v64, v66, v64
	v_add_f32_e32 v65, v67, v65
	v_mfma_f32_32x32x16_bf16 v[0:15], v[68:71], v[72:75], v[0:15]
	v_add_f32_e64 v200, v200, v64
	v_add_f32_e64 v201, v201, v65
	s_cbranch_scc0 .LBB0_1425
